# causal conv pass: next eight rows touched ahead of each batch's loads (cache warm-up)
# speedup vs baseline: 1.0068x; 1.0018x over previous
.LBB0_1030:
	v_readlane_b32 s1, v255, 12
	s_min_i32 s2, s0, s1
	s_ashr_i32 s3, s2, 31
	s_lshl_b64 s[2:3], s[2:3], 11
	s_waitcnt vmcnt(1)
	s_add_i32 s6, s0, 8
	s_ashr_i32 s7, s6, 31
	s_lshl_b64 s[6:7], s[6:7], 11
	v_lshl_add_u64 v[116:117], v[80:81], 0, s[6:7]
	s_mov_b64 s[6:7], 0x1000
	global_load_dwordx4 v[112:115], v[116:117], off
	global_load_dwordx4 v[112:115], v[116:117], off offset:2048
	v_lshl_add_u64 v[116:117], v[116:117], 0, s[6:7]
	global_load_dwordx4 v[112:115], v[116:117], off
	global_load_dwordx4 v[112:115], v[116:117], off offset:2048
	v_lshl_add_u64 v[116:117], v[116:117], 0, s[6:7]
	global_load_dwordx4 v[112:115], v[116:117], off
	global_load_dwordx4 v[112:115], v[116:117], off offset:2048
	v_lshl_add_u64 v[116:117], v[116:117], 0, s[6:7]
	global_load_dwordx4 v[112:115], v[116:117], off
	global_load_dwordx4 v[112:115], v[116:117], off offset:2048
	v_lshl_add_u64 v[40:41], v[80:81], 0, s[2:3]
	s_add_i32 s2, s0, 1
	s_min_i32 s6, s2, s1
	s_ashr_i32 s7, s6, 31
	s_lshl_b64 s[6:7], s[6:7], 11
	s_add_i32 s22, s0, 2
	v_lshl_add_u64 v[42:43], v[80:81], 0, s[6:7]
	s_min_i32 s6, s22, s1
	s_ashr_i32 s7, s6, 31
	s_lshl_b64 s[6:7], s[6:7], 11
	s_add_i32 s18, s0, 3
	global_load_dwordx4 v[68:71], v[40:41], off
	global_load_dwordx4 v[64:67], v[42:43], off
	v_lshl_add_u64 v[40:41], v[80:81], 0, s[6:7]
	s_min_i32 s6, s18, s1
	s_ashr_i32 s7, s6, 31
	s_lshl_b64 s[6:7], s[6:7], 11
	s_add_i32 s16, s0, 4
	v_lshl_add_u64 v[42:43], v[80:81], 0, s[6:7]
	s_min_i32 s6, s16, s1
	s_ashr_i32 s7, s6, 31
	s_lshl_b64 s[6:7], s[6:7], 11
	s_add_i32 s12, s0, 5
	global_load_dwordx4 v[60:63], v[40:41], off
	global_load_dwordx4 v[56:59], v[42:43], off
	v_lshl_add_u64 v[40:41], v[80:81], 0, s[6:7]
	s_min_i32 s6, s12, s1
	s_ashr_i32 s7, s6, 31
	s_lshl_b64 s[6:7], s[6:7], 11
	s_add_i32 s10, s0, 6
	v_lshl_add_u64 v[42:43], v[80:81], 0, s[6:7]
	s_min_i32 s6, s10, s1
	s_ashr_i32 s7, s6, 31
	s_lshl_b64 s[6:7], s[6:7], 11
	s_add_i32 s8, s0, 7
	global_load_dwordx4 v[52:55], v[40:41], off
	global_load_dwordx4 v[48:51], v[42:43], off
	v_lshl_add_u64 v[40:41], v[80:81], 0, s[6:7]
	s_min_i32 s6, s8, s1
	s_ashr_i32 s7, s6, 31
	s_lshl_b64 s[6:7], s[6:7], 11
	v_lshl_add_u64 v[42:43], v[80:81], 0, s[6:7]
	global_load_dwordx4 v[44:47], v[40:41], off
	s_nop 0
	global_load_dwordx4 v[40:43], v[42:43], off
	s_and_b32 s1, s0, 0x3fff
	v_mov_b32_e32 v109, v101
	v_mov_b32_e32 v108, v100
	v_mov_b32_e32 v107, v97
	v_mov_b32_e32 v106, v96
	v_mov_b32_e32 v105, v93
	v_mov_b32_e32 v104, v92
	v_mov_b32_e32 v103, v91
	v_mov_b32_e32 v102, v90
	s_cmp_lg_u32 s1, 0
	v_mov_b32_e32 v100, v72
	v_mov_b32_e32 v101, v73
	v_mov_b32_e32 v96, v78
	v_mov_b32_e32 v97, v79
	v_mov_b32_e32 v92, v76
	v_mov_b32_e32 v93, v77
	v_mov_b32_e32 v90, v74
	v_mov_b32_e32 v91, v75
	v_mov_b32_e32 v72, v86
	v_mov_b32_e32 v73, v87
	v_mov_b32_e32 v78, v88
	v_mov_b32_e32 v79, v89
	v_mov_b32_e32 v76, v94
	v_mov_b32_e32 v77, v95
	v_mov_b32_e32 v74, v98
	v_mov_b32_e32 v75, v99
	s_cbranch_scc1 .LBB0_1032
	v_mov_b32_e32 v100, 0
	v_mov_b32_e32 v101, v100
	v_mov_b32_e32 v96, v100
	v_mov_b32_e32 v97, v100
	v_mov_b32_e32 v92, v100
	v_mov_b32_e32 v93, v100
	v_mov_b32_e32 v90, v100
	v_mov_b32_e32 v91, v100
	v_mov_b32_e32 v72, v100
	v_mov_b32_e32 v73, v100
	v_mov_b32_e32 v78, v100
	v_mov_b32_e32 v79, v100
	v_mov_b32_e32 v76, v100
	v_mov_b32_e32 v77, v100
	v_mov_b32_e32 v74, v100
	v_mov_b32_e32 v75, v100
	v_mov_b32_e32 v102, v100
	v_mov_b32_e32 v103, v100
	v_mov_b32_e32 v104, v100
	v_mov_b32_e32 v105, v100
	v_mov_b32_e32 v106, v100
	v_mov_b32_e32 v107, v100
	v_mov_b32_e32 v108, v100
	v_mov_b32_e32 v109, v100
